# phase-0 scaled weight transpose: 16 loads in flight per trip instead of serialized pairs
# speedup vs baseline: 1.0221x; 1.0028x over previous
; #define LAS __attribute__((address_space(3)))
; __device__ __forceinline__ void transpose_item(const float* W, int K, int N, bf16_t* WT, const float* sk, LAS float* scr, int item, int lane) {
;     const int nblk = N / 32, kb = item / nblk, nb = item % nblk, k0 = 64 * kb, n0 = 32 * nb;
; #pragma unroll 8
;     for (int i = 0; i < 32; ++i) { const int kk = 2 * i + (lane >> 5); float v = W[(size_t)(k0 + kk) * N + n0 + (lane & 31)]; if (sk) v *= sk[k0 + kk]; scr[kk * 33 + (lane & 31)] = v; }
;     asm volatile("s_waitcnt lgkmcnt(0)" ::: "memory");
.LBB0_30:
	v_lshl_add_u64 v[34:35], v[30:31], 0, s[28:29]
	global_load_dword v100, v[34:35], off
	v_lshl_add_u64 v[34:35], v[28:29], 0, s[28:29]
	global_load_dword v101, v[34:35], off
	v_lshl_add_u64 v[34:35], v[26:27], 0, s[28:29]
	global_load_dword v102, v[34:35], off
	v_lshl_add_u64 v[34:35], v[24:25], 0, s[28:29]
	global_load_dword v103, v[34:35], off
	v_lshl_add_u64 v[34:35], v[22:23], 0, s[28:29]
	global_load_dword v104, v[34:35], off
	v_lshl_add_u64 v[34:35], v[20:21], 0, s[28:29]
	global_load_dword v105, v[34:35], off
	v_lshl_add_u64 v[34:35], v[18:19], 0, s[28:29]
	global_load_dword v106, v[34:35], off
	v_lshl_add_u64 v[34:35], v[14:15], 0, s[28:29]
	global_load_dword v107, v[34:35], off
	s_andn2_b64 vcc, exec, s[30:31]
	s_cbranch_vccnz .Lp0tr_nosk
	v_lshl_add_u64 v[34:35], s[24:25], 0, v[32:33]
	global_load_dword v108, v[34:35], off
	v_lshl_add_u64 v[34:35], s[24:25], 0, v[16:17]
	global_load_dword v109, v[34:35], off offset:8
	global_load_dword v110, v[34:35], off offset:16
	global_load_dword v111, v[34:35], off offset:24
	global_load_dword v112, v[34:35], off offset:32
	global_load_dword v113, v[34:35], off offset:40
	global_load_dword v114, v[34:35], off offset:48
	global_load_dword v115, v[34:35], off offset:56
	s_waitcnt vmcnt(0)
	v_mul_f32_e32 v100, v100, v108
	v_mul_f32_e32 v101, v101, v109
	v_mul_f32_e32 v102, v102, v110
	v_mul_f32_e32 v103, v103, v111
	v_mul_f32_e32 v104, v104, v112
	v_mul_f32_e32 v105, v105, v113
	v_mul_f32_e32 v106, v106, v114
	v_mul_f32_e32 v107, v107, v115
	.Lp0tr_nosk:
	s_waitcnt vmcnt(0)
	ds_write_b32 v3, v100
	ds_write_b32 v3, v101 offset:264
	ds_write_b32 v3, v102 offset:528
	ds_write_b32 v3, v103 offset:792
	ds_write_b32 v3, v104 offset:1056
	ds_write_b32 v3, v105 offset:1320
	ds_write_b32 v3, v106 offset:1584
	ds_write_b32 v3, v107 offset:1848
	s_add_u32 s28, s28, 0x90000
	s_addc_u32 s29, s29, 0
	s_add_u32 s24, s24, 64
	s_addc_u32 s25, s25, 0
	s_cmp_lg_u32 s28, 0x240000
	v_add_u32_e32 v3, 0x840, v3
	s_cbranch_scc0 .LBB0_9
	s_branch .LBB0_30
